# last GEMM's plain residual epilogue: residual loads batched 16 deep, all stores after the loads
# speedup vs baseline: 1.0099x; 1.0099x over previous
.LBB0_663:
	v_lshl_add_u32 v144, s15, 8, v146
	v_lshl_or_b32 v142, s14, 8, v148
	v_ashrrev_i32_e32 v145, 31, v144
	v_ashrrev_i32_e32 v143, 31, v142
	v_lshlrev_b64 v[140:141], 10, v[144:145]
	v_lshl_add_u64 v[140:141], v[140:141], 0, v[142:143]
	v_lshlrev_b64 v[140:141], 2, v[140:141]
	v_readlane_b32 s56, v253, 56
	v_readlane_b32 s70, v254, 6
	v_readlane_b32 s71, v254, 7
	s_mov_b64 s[54:55], s[70:71]
	s_mov_b64 s[28:29], -1
	s_and_b64 vcc, exec, s[6:7]
	v_readlane_b32 s57, v253, 57
	v_readlane_b32 s58, v253, 58
	v_readlane_b32 s59, v253, 59
	v_readlane_b32 s60, v253, 60
	v_readlane_b32 s61, v253, 61
	v_readlane_b32 s62, v253, 62
	v_readlane_b32 s63, v253, 63
	v_readlane_b32 s64, v254, 0
	v_readlane_b32 s65, v254, 1
	v_readlane_b32 s66, v254, 2
	v_readlane_b32 s67, v254, 3
	v_readlane_b32 s68, v254, 4
	v_readlane_b32 s69, v254, 5
	s_mov_b64 s[14:15], s[16:17]
	global_load_dwordx4 v[150:153], v140, s[14:15]
	global_load_dwordx4 v[154:157], v140, s[14:15] offset:16
	global_load_dwordx4 v[158:161], v140, s[14:15] offset:512
	global_load_dwordx4 v[166:169], v140, s[14:15] offset:528
	s_add_u32 s14, s16, 0x10000
	s_addc_u32 s15, s17, 0
	global_load_dwordx4 v[170:173], v140, s[14:15]
	global_load_dwordx4 v[174:177], v140, s[14:15] offset:16
	global_load_dwordx4 v[178:181], v140, s[14:15] offset:512
	global_load_dwordx4 v[182:185], v140, s[14:15] offset:528
	s_add_u32 s14, s16, 0x20000
	s_addc_u32 s15, s17, 0
	global_load_dwordx4 v[186:189], v140, s[14:15]
	global_load_dwordx4 v[190:193], v140, s[14:15] offset:16
	global_load_dwordx4 v[194:197], v140, s[14:15] offset:512
	global_load_dwordx4 v[198:201], v140, s[14:15] offset:528
	s_add_u32 s14, s16, 0x30000
	s_addc_u32 s15, s17, 0
	global_load_dwordx4 v[210:213], v140, s[14:15]
	global_load_dwordx4 v[214:217], v140, s[14:15] offset:16
	global_load_dwordx4 v[218:221], v140, s[14:15] offset:512
	global_load_dwordx4 v[142:145], v140, s[14:15] offset:528
	s_waitcnt vmcnt(12)
	v_pk_fma_f32 v[126:127], s[18:19], v[126:127], v[150:151]
	v_pk_fma_f32 v[128:129], s[22:23], v[128:129], v[152:153]
	v_pk_fma_f32 v[122:123], s[18:19], v[122:123], v[154:155]
	v_pk_fma_f32 v[124:125], s[22:23], v[124:125], v[156:157]
	v_pk_fma_f32 v[118:119], s[18:19], v[118:119], v[158:159]
	v_pk_fma_f32 v[120:121], s[22:23], v[120:121], v[160:161]
	v_pk_fma_f32 v[114:115], s[18:19], v[114:115], v[166:167]
	v_pk_fma_f32 v[116:117], s[22:23], v[116:117], v[168:169]
	s_add_u32 s14, s16, 0x80000
	s_addc_u32 s15, s17, 0
	global_load_dwordx4 v[150:153], v140, s[14:15]
	global_load_dwordx4 v[154:157], v140, s[14:15] offset:16
	global_load_dwordx4 v[158:161], v140, s[14:15] offset:512
	global_load_dwordx4 v[166:169], v140, s[14:15] offset:528
	s_waitcnt vmcnt(12)
	v_pk_fma_f32 v[110:111], s[18:19], v[110:111], v[170:171]
	v_pk_fma_f32 v[112:113], s[22:23], v[112:113], v[172:173]
	v_pk_fma_f32 v[106:107], s[18:19], v[106:107], v[174:175]
	v_pk_fma_f32 v[108:109], s[22:23], v[108:109], v[176:177]
	v_pk_fma_f32 v[102:103], s[18:19], v[102:103], v[178:179]
	v_pk_fma_f32 v[104:105], s[22:23], v[104:105], v[180:181]
	v_pk_fma_f32 v[98:99], s[18:19], v[98:99], v[182:183]
	v_pk_fma_f32 v[100:101], s[22:23], v[100:101], v[184:185]
	s_add_u32 s14, s16, 0x90000
	s_addc_u32 s15, s17, 0
	global_load_dwordx4 v[170:173], v140, s[14:15]
	global_load_dwordx4 v[174:177], v140, s[14:15] offset:16
	global_load_dwordx4 v[178:181], v140, s[14:15] offset:512
	global_load_dwordx4 v[182:185], v140, s[14:15] offset:528
	s_waitcnt vmcnt(12)
	v_pk_fma_f32 v[94:95], s[18:19], v[94:95], v[186:187]
	v_pk_fma_f32 v[96:97], s[22:23], v[96:97], v[188:189]
	v_pk_fma_f32 v[90:91], s[18:19], v[90:91], v[190:191]
	v_pk_fma_f32 v[92:93], s[22:23], v[92:93], v[192:193]
	v_pk_fma_f32 v[86:87], s[18:19], v[86:87], v[194:195]
	v_pk_fma_f32 v[88:89], s[22:23], v[88:89], v[196:197]
	v_pk_fma_f32 v[82:83], s[18:19], v[82:83], v[198:199]
	v_pk_fma_f32 v[84:85], s[22:23], v[84:85], v[200:201]
	s_add_u32 s14, s16, 0xa0000
	s_addc_u32 s15, s17, 0
	global_load_dwordx4 v[186:189], v140, s[14:15]
	global_load_dwordx4 v[190:193], v140, s[14:15] offset:16
	global_load_dwordx4 v[194:197], v140, s[14:15] offset:512
	global_load_dwordx4 v[198:201], v140, s[14:15] offset:528
	s_waitcnt vmcnt(12)
	v_pk_fma_f32 v[78:79], s[18:19], v[78:79], v[210:211]
	v_pk_fma_f32 v[80:81], s[22:23], v[80:81], v[212:213]
	v_pk_fma_f32 v[74:75], s[18:19], v[74:75], v[214:215]
	v_pk_fma_f32 v[76:77], s[22:23], v[76:77], v[216:217]
	v_pk_fma_f32 v[70:71], s[18:19], v[70:71], v[218:219]
	v_pk_fma_f32 v[72:73], s[22:23], v[72:73], v[220:221]
	v_pk_fma_f32 v[66:67], s[18:19], v[66:67], v[142:143]
	v_pk_fma_f32 v[68:69], s[22:23], v[68:69], v[144:145]
	s_add_u32 s14, s16, 0xb0000
	s_addc_u32 s15, s17, 0
	global_load_dwordx4 v[210:213], v140, s[14:15]
	global_load_dwordx4 v[214:217], v140, s[14:15] offset:16
	global_load_dwordx4 v[218:221], v140, s[14:15] offset:512
	global_load_dwordx4 v[142:145], v140, s[14:15] offset:528
	s_waitcnt vmcnt(12)
	v_pk_fma_f32 v[62:63], s[18:19], v[62:63], v[150:151]
	v_pk_fma_f32 v[64:65], s[22:23], v[64:65], v[152:153]
	v_pk_fma_f32 v[58:59], s[18:19], v[58:59], v[154:155]
	v_pk_fma_f32 v[60:61], s[22:23], v[60:61], v[156:157]
	v_pk_fma_f32 v[54:55], s[18:19], v[54:55], v[158:159]
	v_pk_fma_f32 v[56:57], s[22:23], v[56:57], v[160:161]
	v_pk_fma_f32 v[50:51], s[18:19], v[50:51], v[166:167]
	v_pk_fma_f32 v[52:53], s[22:23], v[52:53], v[168:169]
	s_waitcnt vmcnt(8)
	v_pk_fma_f32 v[46:47], s[18:19], v[46:47], v[170:171]
	v_pk_fma_f32 v[48:49], s[22:23], v[48:49], v[172:173]
	v_pk_fma_f32 v[42:43], s[18:19], v[42:43], v[174:175]
	v_pk_fma_f32 v[44:45], s[22:23], v[44:45], v[176:177]
	v_pk_fma_f32 v[38:39], s[18:19], v[38:39], v[178:179]
	v_pk_fma_f32 v[40:41], s[22:23], v[40:41], v[180:181]
	v_pk_fma_f32 v[34:35], s[18:19], v[34:35], v[182:183]
	v_pk_fma_f32 v[36:37], s[22:23], v[36:37], v[184:185]
	s_waitcnt vmcnt(4)
	v_pk_fma_f32 v[30:31], s[18:19], v[30:31], v[186:187]
	v_pk_fma_f32 v[32:33], s[22:23], v[32:33], v[188:189]
	v_pk_fma_f32 v[26:27], s[18:19], v[26:27], v[190:191]
	v_pk_fma_f32 v[28:29], s[22:23], v[28:29], v[192:193]
	v_pk_fma_f32 v[22:23], s[18:19], v[22:23], v[194:195]
	v_pk_fma_f32 v[24:25], s[22:23], v[24:25], v[196:197]
	v_pk_fma_f32 v[18:19], s[18:19], v[18:19], v[198:199]
	v_pk_fma_f32 v[20:21], s[22:23], v[20:21], v[200:201]
	s_waitcnt vmcnt(0)
	v_pk_fma_f32 v[14:15], s[18:19], v[14:15], v[210:211]
	v_pk_fma_f32 v[16:17], s[22:23], v[16:17], v[212:213]
	v_pk_fma_f32 v[10:11], s[18:19], v[10:11], v[214:215]
	v_pk_fma_f32 v[12:13], s[22:23], v[12:13], v[216:217]
	v_pk_fma_f32 v[6:7], s[18:19], v[6:7], v[218:219]
	v_pk_fma_f32 v[8:9], s[22:23], v[8:9], v[220:221]
	v_pk_fma_f32 v[2:3], s[18:19], v[2:3], v[142:143]
	v_pk_fma_f32 v[4:5], s[22:23], v[4:5], v[144:145]
	v_mov_b32_e32 v142, v140
	global_store_dwordx4 v142, v[126:129], s[54:55] nt
	global_store_dwordx4 v142, v[122:125], s[54:55] offset:16 nt
	global_store_dwordx4 v142, v[118:121], s[54:55] offset:512 nt
	global_store_dwordx4 v142, v[114:117], s[54:55] offset:528 nt
	v_add_u32_e32 v142, 0x10000, v140
	global_store_dwordx4 v142, v[110:113], s[54:55] nt
	global_store_dwordx4 v142, v[106:109], s[54:55] offset:16 nt
	global_store_dwordx4 v142, v[102:105], s[54:55] offset:512 nt
	global_store_dwordx4 v142, v[98:101], s[54:55] offset:528 nt
	v_add_u32_e32 v142, 0x20000, v140
	global_store_dwordx4 v142, v[94:97], s[54:55] nt
	global_store_dwordx4 v142, v[90:93], s[54:55] offset:16 nt
	global_store_dwordx4 v142, v[86:89], s[54:55] offset:512 nt
	global_store_dwordx4 v142, v[82:85], s[54:55] offset:528 nt
	v_add_u32_e32 v142, 0x30000, v140
	global_store_dwordx4 v142, v[78:81], s[54:55] nt
	global_store_dwordx4 v142, v[74:77], s[54:55] offset:16 nt
	global_store_dwordx4 v142, v[70:73], s[54:55] offset:512 nt
	global_store_dwordx4 v142, v[66:69], s[54:55] offset:528 nt
	v_add_u32_e32 v142, 0x80000, v140
	global_store_dwordx4 v142, v[62:65], s[54:55] nt
	global_store_dwordx4 v142, v[58:61], s[54:55] offset:16 nt
	global_store_dwordx4 v142, v[54:57], s[54:55] offset:512 nt
	global_store_dwordx4 v142, v[50:53], s[54:55] offset:528 nt
	v_add_u32_e32 v142, 0x90000, v140
	global_store_dwordx4 v142, v[46:49], s[54:55] nt
	global_store_dwordx4 v142, v[42:45], s[54:55] offset:16 nt
	global_store_dwordx4 v142, v[38:41], s[54:55] offset:512 nt
	global_store_dwordx4 v142, v[34:37], s[54:55] offset:528 nt
	v_add_u32_e32 v142, 0xa0000, v140
	global_store_dwordx4 v142, v[30:33], s[54:55] nt
	global_store_dwordx4 v142, v[26:29], s[54:55] offset:16 nt
	global_store_dwordx4 v142, v[22:25], s[54:55] offset:512 nt
	global_store_dwordx4 v142, v[18:21], s[54:55] offset:528 nt
	v_add_u32_e32 v142, 0xb0000, v140
	global_store_dwordx4 v142, v[14:17], s[54:55] nt
	global_store_dwordx4 v142, v[10:13], s[54:55] offset:16 nt
	global_store_dwordx4 v142, v[6:9], s[54:55] offset:512 nt
	global_store_dwordx4 v142, v[2:5], s[54:55] offset:528 nt
	s_mov_b64 s[14:15], 0xb0000
	s_cbranch_vccnz .LBB0_648
	s_andn2_b64 vcc, exec, s[10:11]
	s_cbranch_vccnz .LBB0_647
	s_barrier
	s_branch .LBB0_647
